# static s_setprio 1 for waves 4-7 for the whole mixer phase (reset at phase exit)
# baseline (speedup 1.0000x reference)
; __device__ __forceinline__ void phase_mixer(const Params& p, unsigned char* sm, const int TIDX, const int BIDX, const int rep) {
;     unsigned* ctr = (unsigned*)(p.ws + WS_CTL) + 64 * rep;
;     int* sitem = (int*)(sm + LDS_BYTES - 16);
; __global__ __launch_bounds__(512, 2) void mega(Params p_unused, int ph_lo_unused, int ph_hi_unused, int rep_unused, int pad_unused) {
;     ...
;         else if (ph == 6 && (PHSEL & 64)) phase_mixer(p, shm, TIDX, BIDX, rep);
.LBB0_36:
	s_and_b64 vcc, exec, s[8:9]
	s_cbranch_vccz .LBB0_191
	s_cmp_lt_i32 s48, 7
	s_mov_b64 s[4:5], -1
	s_waitcnt lgkmcnt(0)
	s_mov_b32 s16, 0x8000
	s_mov_b32 s17, 0xc000
	s_mov_b32 s18, 0x10000
	s_mov_b32 s19, 0x18000
	s_mov_b32 s20, 0x1c000
	s_mov_b32 s21, 0x20000
	s_mov_b32 s22, 0x24000
	s_mov_b32 s23, 0x2c000
	s_cbranch_scc0 .LBB0_190
	s_load_dwordx16 s[52:67], s[68:69], 0xc0
	s_lshl_b64 s[4:5], s[6:7], 2
	v_cmp_lt_i32_e32 vcc, v193, v188
	v_cmp_eq_u32_e64 s[42:43], 0, v199
	s_waitcnt lgkmcnt(0)
	s_add_u32 s2, s66, s4
	s_addc_u32 s3, s67, s5
	v_writelane_b32 v255, s2, 37
	s_add_u32 s0, s64, 0xd200000
	v_cndmask_b32_e32 v0, v169, v193, vcc
	v_writelane_b32 v255, s3, 38
	v_writelane_b32 v255, s0, 49
	s_addc_u32 s0, s65, 0
	s_add_u32 s2, s64, 0xc400000
	v_writelane_b32 v255, s0, 47
	s_addc_u32 s0, s65, 0
	s_add_u32 s4, s66, 0x12004000
	v_writelane_b32 v255, s0, 57
	s_addc_u32 s5, s67, 0
	v_writelane_b32 v255, s4, 58
	s_add_u32 s0, s66, 0x161e4000
	v_cmp_lt_i32_e32 vcc, v194, v188
	v_writelane_b32 v255, s5, 59
	v_writelane_b32 v255, s0, 39
	s_addc_u32 s0, s67, 0
	s_add_u32 s4, s66, 0x10f84000
	s_addc_u32 s5, s67, 0
	v_writelane_b32 v255, s0, 40
	s_add_u32 s40, s66, 0x1104000
	v_writelane_b32 v255, s4, 53
	s_addc_u32 s41, s67, 0
	v_lshlrev_b32_e32 v186, 2, v0
	v_writelane_b32 v255, s5, 54
	s_add_u32 s4, s66, 0x1afe4000
	s_addc_u32 s5, s67, 0
	s_add_u32 s0, s66, 0xee84000
	v_writelane_b32 v255, s0, 41
	s_addc_u32 s0, s67, 0
	v_writelane_b32 v255, s0, 42
	s_add_u32 s0, s66, 0x4000
	s_addc_u32 s3, s67, 0
	s_add_u32 s79, s66, 0x2204000
	s_addc_u32 s80, s67, 0
	s_add_u32 s6, s66, 0x3304000
	s_addc_u32 s7, s67, 0
	v_writelane_b32 v255, s6, 55
	v_cndmask_b32_e32 v0, v169, v194, vcc
	v_cmp_lt_i32_e32 vcc, v189, v188
	v_writelane_b32 v255, s7, 56
	s_add_u32 s6, s66, 0x6284000
	v_writelane_b32 v255, s6, 36
	s_addc_u32 s6, s67, 0
	v_writelane_b32 v255, s6, 43
	s_add_u32 s6, s66, 0x1fce4000
	s_addc_u32 s7, s67, 0
	v_lshlrev_b32_e32 v187, 2, v0
	v_cndmask_b32_e32 v0, v169, v189, vcc
	v_cmp_lt_i32_e32 vcc, v190, v188
	v_writelane_b32 v255, s6, 51
	v_lshlrev_b32_e32 v200, 2, v0
	v_cndmask_b32_e32 v0, v169, v190, vcc
	v_cmp_lt_i32_e32 vcc, v191, v188
	v_writelane_b32 v255, s7, 52
	s_add_u32 s6, s66, 0x1d1e4000
	v_lshlrev_b32_e32 v201, 2, v0
	v_cndmask_b32_e32 v0, v169, v191, vcc
	v_cmp_lt_i32_e32 vcc, v192, v188
	s_addc_u32 s7, s67, 0
	v_lshlrev_b32_e32 v202, 2, v0
	v_cndmask_b32_e32 v0, v169, v192, vcc
	v_writelane_b32 v255, s6, 45
	v_lshlrev_b32_e32 v203, 2, v0
	s_nop 0
	v_writelane_b32 v255, s7, 46
	v_readlane_b32 s6, v254, 3
	s_nop 3
	s_cmp_ge_u32 s6, 4
	s_cbranch_scc0 .Lmix_prio_done
	s_setprio 1
.Lmix_prio_done:
	s_branch .LBB0_42
.LBB0_39:
	s_or_b64 exec, exec, s[6:7]
	s_mov_b32 s76, 0x30000
	s_mov_b32 s73, 0x34000
	s_mov_b32 s86, 0x38000
	s_mov_b32 s77, 0x40000
	s_mov_b32 s92, 0x64000
	s_mov_b32 s85, 0x78000
	s_movk_i32 s74, 0x110
	s_movk_i32 s81, 0x3fff
	s_movk_i32 s84, 0x2100
	s_mov_b64 s[42:43], s[46:47]
	s_mov_b32 s2, s51

; __global__ __launch_bounds__(512, 2) void mega(Params p_unused, int ph_lo_unused, int ph_hi_unused, int rep_unused, int pad_unused) {
;     ...
;         else if (ph == 6 && (PHSEL & 64)) phase_mixer(p, shm, TIDX, BIDX, rep);
;         else if (ph == 8 && (PHSEL & 8)) phase_norm(p, shm, 1, TIDX, BIDX);
;         else if (ph == 11 && (PHSEL & 8)) phase_norm(p, shm, 2, TIDX, BIDX);
;         if (ph + 1 < ph_hi) { if (ph_hi < 0) cg::this_grid().sync(); else xcd_barrier((unsigned*)(p.ws + WS_CTL), xst, TIDX); }
.LBB0_189:
	s_setprio 0
	s_mov_b64 s[4:5], 0
